# P0: once-read inputs (f32 weights, x) loaded with the nt (streaming) cache policy
# speedup vs baseline: 1.0113x; 1.0113x over previous
; #define LAS __attribute__((address_space(3)))
; #define LDS_WAIT() asm volatile("s_waitcnt lgkmcnt(0)" ::: "memory")
; __device__ __forceinline__ void p0_transpose_item(const float* W, int K, int N, bf16_t* WT, LAS float* scr, int item, int lane, const float* kscale) {
;     const int nblk = N / 32, kb = item / nblk, nb = item % nblk, k0 = 64 * kb, n0 = 32 * nb;
; #pragma unroll 8
;     for (int i = 0; i < 32; ++i) { const int kk = 2 * i + (lane >> 5); scr[kk * 33 + (lane & 31)] = W[(size_t)(k0 + kk) * N + n0 + (lane & 31)] * (kscale ? kscale[k0 + kk] : 1.0f); }
;     LDS_WAIT(); asm volatile("" ::: "memory");
; __global__ void __launch_bounds__(512, 2) mk_fwd(Params p) {
;     ...
;                 else p0_transpose_item(p.w_out + (size_t)l * DM * DM, DM, DM, W2T + (size_t)l * DM * DM, scr, r - I1, lane, nullptr);
.LBB0_226:
	s_mul_hi_i32 s0, s4, 0x78787879
	s_lshr_b32 s1, s0, 31
	s_ashr_i32 s0, s0, 12
	s_add_i32 s2, s0, s1
	s_mul_i32 s0, s2, 0x2200
	s_sub_i32 s5, s4, s0
	s_ashr_i32 s3, s2, 31
	s_cmpk_gt_i32 s5, 0x19ff
	s_mov_b64 s[0:1], -1
	s_cbranch_scc0 .LBB0_230
	s_lshl_b64 s[0:1], s[2:3], 22
	s_lshl_b64 s[6:7], s[2:3], 24
	s_add_u32 s8, s66, s6
	s_addc_u32 s9, s67, s7
	s_add_i32 s6, s5, 0xe600
	s_and_b32 s7, s6, 0xffc0
	s_lshl_b32 s6, s5, 5
	s_and_b32 s6, s6, 0x7e0
	s_lshl_b32 s10, s6, 2
	s_add_u32 s8, s8, s10
	s_addc_u32 s9, s9, 0
	v_mov_b32_e32 v13, v1
	v_lshl_add_u64 v[14:15], s[8:9], 0, v[12:13]
	v_or_b32_e32 v5, s7, v3
	v_or_b32_e32 v16, s7, v4
	s_lshl_b32 s10, s7, 13
	s_add_u32 s8, s8, s10
	s_addc_u32 s9, s9, 0
	v_lshlrev_b32_e32 v47, 13, v4
	v_add_u32_e32 v47, v47, v12
	global_load_dword v100, v47, s[8:9] nt
	s_add_u32 s8, s8, 0x4000
	s_addc_u32 s9, s9, 0
	global_load_dword v101, v47, s[8:9] nt
	s_add_u32 s8, s8, 0x4000
	s_addc_u32 s9, s9, 0
	global_load_dword v102, v47, s[8:9] nt
	s_add_u32 s8, s8, 0x4000
	s_addc_u32 s9, s9, 0
	global_load_dword v103, v47, s[8:9] nt
	s_add_u32 s8, s8, 0x4000
	s_addc_u32 s9, s9, 0
	global_load_dword v104, v47, s[8:9] nt
	s_add_u32 s8, s8, 0x4000
	s_addc_u32 s9, s9, 0
	global_load_dword v105, v47, s[8:9] nt
	s_add_u32 s8, s8, 0x4000
	s_addc_u32 s9, s9, 0
	global_load_dword v106, v47, s[8:9] nt
	s_add_u32 s8, s8, 0x4000
	s_addc_u32 s9, s9, 0
	global_load_dword v107, v47, s[8:9] nt
	s_add_u32 s8, s8, 0x4000
	s_addc_u32 s9, s9, 0
	global_load_dword v108, v47, s[8:9] nt
	s_add_u32 s8, s8, 0x4000
	s_addc_u32 s9, s9, 0
	global_load_dword v109, v47, s[8:9] nt
	s_add_u32 s8, s8, 0x4000
	s_addc_u32 s9, s9, 0
	global_load_dword v110, v47, s[8:9] nt
	s_add_u32 s8, s8, 0x4000
	s_addc_u32 s9, s9, 0
	global_load_dword v111, v47, s[8:9] nt
	s_add_u32 s8, s8, 0x4000
	s_addc_u32 s9, s9, 0
	global_load_dword v112, v47, s[8:9] nt
	s_add_u32 s8, s8, 0x4000
	s_addc_u32 s9, s9, 0
	global_load_dword v113, v47, s[8:9] nt
	s_add_u32 s8, s8, 0x4000
	s_addc_u32 s9, s9, 0
	global_load_dword v114, v47, s[8:9] nt
	s_add_u32 s8, s8, 0x4000
	s_addc_u32 s9, s9, 0
	global_load_dword v115, v47, s[8:9] nt
	s_add_u32 s8, s8, 0x4000
	s_addc_u32 s9, s9, 0
	global_load_dword v116, v47, s[8:9] nt
	s_add_u32 s8, s8, 0x4000
	s_addc_u32 s9, s9, 0
	global_load_dword v117, v47, s[8:9] nt
	s_add_u32 s8, s8, 0x4000
	s_addc_u32 s9, s9, 0
	global_load_dword v118, v47, s[8:9] nt
	s_add_u32 s8, s8, 0x4000
	s_addc_u32 s9, s9, 0
	global_load_dword v119, v47, s[8:9] nt
	s_add_u32 s8, s8, 0x4000
	s_addc_u32 s9, s9, 0
	global_load_dword v120, v47, s[8:9] nt
	s_add_u32 s8, s8, 0x4000
	s_addc_u32 s9, s9, 0
	global_load_dword v121, v47, s[8:9] nt
	s_add_u32 s8, s8, 0x4000
	s_addc_u32 s9, s9, 0
	global_load_dword v122, v47, s[8:9] nt
	s_add_u32 s8, s8, 0x4000
	s_addc_u32 s9, s9, 0
	global_load_dword v123, v47, s[8:9] nt
	s_add_u32 s8, s8, 0x4000
	s_addc_u32 s9, s9, 0
	global_load_dword v124, v47, s[8:9] nt
	s_add_u32 s8, s8, 0x4000
	s_addc_u32 s9, s9, 0
	global_load_dword v125, v47, s[8:9] nt
	s_add_u32 s8, s8, 0x4000
	s_addc_u32 s9, s9, 0
	global_load_dword v126, v47, s[8:9] nt
	s_add_u32 s8, s8, 0x4000
	s_addc_u32 s9, s9, 0
	global_load_dword v127, v47, s[8:9] nt
	s_add_u32 s8, s8, 0x4000
	s_addc_u32 s9, s9, 0
	global_load_dword v128, v47, s[8:9] nt
	s_add_u32 s8, s8, 0x4000
	s_addc_u32 s9, s9, 0
	global_load_dword v129, v47, s[8:9] nt
	s_add_u32 s8, s8, 0x4000
	s_addc_u32 s9, s9, 0
	global_load_dword v130, v47, s[8:9] nt
	s_add_u32 s8, s8, 0x4000
	s_addc_u32 s9, s9, 0
	global_load_dword v131, v47, s[8:9] nt
	s_waitcnt vmcnt(31)
	ds_write_b32 v39, v100 offset:0
	s_waitcnt vmcnt(30)
	ds_write_b32 v39, v101 offset:264
	s_waitcnt vmcnt(29)
	ds_write_b32 v39, v102 offset:528
	s_waitcnt vmcnt(28)
	ds_write_b32 v39, v103 offset:792
	s_waitcnt vmcnt(27)
	ds_write_b32 v39, v104 offset:1056
	s_waitcnt vmcnt(26)
	ds_write_b32 v39, v105 offset:1320
	s_waitcnt vmcnt(25)
	ds_write_b32 v39, v106 offset:1584
	s_waitcnt vmcnt(24)
	ds_write_b32 v39, v107 offset:1848
	s_waitcnt vmcnt(23)
	ds_write_b32 v39, v108 offset:2112
	s_waitcnt vmcnt(22)
	ds_write_b32 v39, v109 offset:2376
	s_waitcnt vmcnt(21)
	ds_write_b32 v39, v110 offset:2640
	s_waitcnt vmcnt(20)
	ds_write_b32 v39, v111 offset:2904
	s_waitcnt vmcnt(19)
	ds_write_b32 v39, v112 offset:3168
	s_waitcnt vmcnt(18)
	ds_write_b32 v39, v113 offset:3432
	s_waitcnt vmcnt(17)
	ds_write_b32 v39, v114 offset:3696
	s_waitcnt vmcnt(16)
	ds_write_b32 v39, v115 offset:3960
	s_waitcnt vmcnt(15)
	ds_write_b32 v39, v116 offset:4224
	s_waitcnt vmcnt(14)
	ds_write_b32 v39, v117 offset:4488
	s_waitcnt vmcnt(13)
	ds_write_b32 v39, v118 offset:4752
	s_waitcnt vmcnt(12)
	ds_write_b32 v39, v119 offset:5016
	s_waitcnt vmcnt(11)
	ds_write_b32 v39, v120 offset:5280
	s_waitcnt vmcnt(10)
	ds_write_b32 v39, v121 offset:5544
	s_waitcnt vmcnt(9)
	ds_write_b32 v39, v122 offset:5808
	s_waitcnt vmcnt(8)
	ds_write_b32 v39, v123 offset:6072
	s_waitcnt vmcnt(7)
	ds_write_b32 v39, v124 offset:6336
	s_waitcnt vmcnt(6)
	ds_write_b32 v39, v125 offset:6600
	s_waitcnt vmcnt(5)
	ds_write_b32 v39, v126 offset:6864
	s_waitcnt vmcnt(4)
	ds_write_b32 v39, v127 offset:7128
	s_waitcnt vmcnt(3)
	ds_write_b32 v39, v128 offset:7392
	s_waitcnt vmcnt(2)
	ds_write_b32 v39, v129 offset:7656
	s_waitcnt vmcnt(1)
	ds_write_b32 v39, v130 offset:7920
	s_waitcnt vmcnt(0)
	ds_write_b32 v39, v131 offset:8184
	s_lshl_b64 s[0:1], s[0:1], 1
	s_add_u32 s0, s96, s0
	s_waitcnt lgkmcnt(0)
; #define LAS __attribute__((address_space(3)))
; #define LDS_WAIT() asm volatile("s_waitcnt lgkmcnt(0)" ::: "memory")
; __device__ __forceinline__ unsigned pk2(float lo, float hi) { unsigned r; asm("v_cvt_pk_bf16_f32 %0, %1, %2" : "=v"(r) : "v"(lo), "v"(hi)); return r; }
; __device__ __forceinline__ void p0_transpose_item(const float* W, int K, int N, bf16_t* WT, LAS float* scr, int item, int lane, const float* kscale) {
;     const int nblk = N / 32, kb = item / nblk, nb = item % nblk, k0 = 64 * kb, n0 = 32 * nb;
; #pragma unroll 8
;     for (int i = 0; i < 32; ++i) { const int kk = 2 * i + (lane >> 5); scr[kk * 33 + (lane & 31)] = W[(size_t)(k0 + kk) * N + n0 + (lane & 31)] * (kscale ? kscale[k0 + kk] : 1.0f); }
;     ...
;     const int c = lane & 7;
; #pragma unroll
;     for (int j = 0; j < 4; ++j) { const int n = (lane >> 3) + 8 * j; const LAS float* s = scr + (8 * c) * 33 + n;
;         v4u o; o.x = pk2(s[0 * 33], s[1 * 33]); o.y = pk2(s[2 * 33], s[3 * 33]); o.z = pk2(s[4 * 33], s[5 * 33]); o.w = pk2(s[6 * 33], s[7 * 33]);
;         *(v4u*)(WT + (size_t)(n0 + n) * K + k0 + 8 * c) = o; }
;     LDS_WAIT(); asm volatile("" ::: "memory");
	s_addc_u32 s1, s97, s1
	s_lshl_b32 s7, s7, 1
	s_add_u32 s0, s0, s7
	ds_read2_b32 v[18:19], v9 offset0:33 offset1:41
	ds_read2_b32 v[20:21], v9 offset1:8
	ds_read2_b32 v[22:23], v9 offset0:66 offset1:74
	ds_read2_b32 v[24:25], v9 offset0:99 offset1:107
	ds_read2_b32 v[26:27], v9 offset0:132 offset1:140
	ds_read2_b32 v[28:29], v9 offset0:165 offset1:173
	ds_read2_b32 v[30:31], v9 offset0:198 offset1:206
	ds_read2_b32 v[32:33], v9 offset0:231 offset1:239
	s_addc_u32 s1, s1, 0
	v_lshlrev_b32_e32 v0, 1, v8
	v_lshl_add_u64 v[34:35], s[0:1], 0, v[0:1]
	v_or_b32_e32 v0, s6, v7
	v_lshlrev_b32_e32 v0, 12, v0
	v_lshl_add_u64 v[48:49], v[34:35], 0, v[0:1]
	s_waitcnt lgkmcnt(6)
	v_cvt_pk_bf16_f32 v14, v20, v18
	s_waitcnt lgkmcnt(4)
	v_cvt_pk_bf16_f32 v15, v22, v24
	s_waitcnt lgkmcnt(2)
	v_cvt_pk_bf16_f32 v16, v26, v28
	s_waitcnt lgkmcnt(0)
	v_cvt_pk_bf16_f32 v17, v30, v32
	global_store_dwordx4 v[48:49], v[14:17], off
	v_or_b32_e32 v0, s6, v36
	v_lshlrev_b32_e32 v0, 12, v0
	v_cvt_pk_bf16_f32 v14, v21, v19
	v_cvt_pk_bf16_f32 v15, v23, v25
	v_cvt_pk_bf16_f32 v16, v27, v29
	v_cvt_pk_bf16_f32 v17, v31, v33
	ds_read2_b32 v[20:21], v9 offset0:16 offset1:24
	ds_read2_b32 v[22:23], v9 offset0:49 offset1:57
	ds_read2_b32 v[24:25], v9 offset0:82 offset1:90
	ds_read2_b32 v[26:27], v9 offset0:115 offset1:123
	ds_read2_b32 v[28:29], v9 offset0:148 offset1:156
	ds_read2_b32 v[30:31], v9 offset0:181 offset1:189
	ds_read2_b32 v[32:33], v9 offset0:214 offset1:222
	ds_read2_b32 v[48:49], v9 offset0:247 offset1:255
	v_lshl_add_u64 v[18:19], v[34:35], 0, v[0:1]
	v_or_b32_e32 v0, s6, v37
	v_lshlrev_b32_e32 v0, 12, v0
	global_store_dwordx4 v[18:19], v[14:17], off
	v_lshl_add_u64 v[18:19], v[34:35], 0, v[0:1]
	v_or_b32_e32 v0, s6, v38
	v_lshlrev_b32_e32 v0, 12, v0
	s_waitcnt lgkmcnt(6)
	v_cvt_pk_bf16_f32 v14, v20, v22
	s_waitcnt lgkmcnt(4)
	v_cvt_pk_bf16_f32 v15, v24, v26
	s_waitcnt lgkmcnt(2)
	v_cvt_pk_bf16_f32 v16, v28, v30
	s_waitcnt lgkmcnt(0)
	v_cvt_pk_bf16_f32 v17, v32, v48
	global_store_dwordx4 v[18:19], v[14:17], off
	v_lshl_add_u64 v[18:19], v[34:35], 0, v[0:1]
	s_nop 0
	v_cvt_pk_bf16_f32 v14, v21, v23
	v_cvt_pk_bf16_f32 v15, v25, v27
	v_cvt_pk_bf16_f32 v16, v29, v31
	v_cvt_pk_bf16_f32 v17, v33, v49
	global_store_dwordx4 v[18:19], v[14:17], off
	s_waitcnt lgkmcnt(0)
	s_branch .LBB0_225
.LBB0_230:
	s_and_b64 vcc, exec, s[0:1]
	s_cbranch_vccz .LBB0_225
	s_lshl_b64 s[0:1], s[2:3], 13
	s_add_u32 s18, s54, s0
	s_mul_i32 s0, s5, 0x4ec5
	s_addc_u32 s19, s55, s1
	s_lshr_b32 s1, s0, 31
	s_ashr_i32 s0, s0, 22
	s_add_i32 s0, s0, s1
	s_mul_i32 s1, s0, 0xd0
	s_sub_i32 s1, s5, s1
	s_sext_i32_i16 s1, s1
	s_lshl_b32 s16, s1, 5
	s_lshl_b32 s20, s0, 6
	s_ashr_i32 s17, s16, 31
	s_mul_i32 s7, s2, 0x3400000
	s_ashr_i32 s21, s20, 31
	s_lshl_b64 s[0:1], s[16:17], 2
	s_mul_hi_i32 s6, s2, 0x3400000
	s_add_u32 s0, s0, s7
	s_addc_u32 s1, s1, s6
	s_mul_i32 s8, s20, 0x6800
	s_add_u32 s6, s56, s0
	s_addc_u32 s7, s57, s1
	s_add_u32 s6, s6, s8
	s_addc_u32 s7, s7, 0
	v_mov_b32_e32 v47, 0x6800
	v_mad_u32_u24 v47, v4, v47, v12
	v_or_b32_e32 v32, s20, v4
	v_lshlrev_b32_e32 v32, 2, v32
	v_mov_b32_e32 v33, v1
	v_lshl_add_u64 v[32:33], s[18:19], 0, v[32:33]
	global_load_dword v100, v47, s[6:7] nt
	s_add_u32 s6, s6, 0xd000
	s_addc_u32 s7, s7, 0
	global_load_dword v132, v[32:33], off offset:0
	global_load_dword v101, v47, s[6:7] nt
	s_add_u32 s6, s6, 0xd000
	s_addc_u32 s7, s7, 0
	global_load_dword v133, v[32:33], off offset:8
	global_load_dword v102, v47, s[6:7] nt
	s_add_u32 s6, s6, 0xd000
	s_addc_u32 s7, s7, 0
	global_load_dword v134, v[32:33], off offset:16
	global_load_dword v103, v47, s[6:7] nt
	s_add_u32 s6, s6, 0xd000
	s_addc_u32 s7, s7, 0
	global_load_dword v135, v[32:33], off offset:24
	global_load_dword v104, v47, s[6:7] nt
	s_add_u32 s6, s6, 0xd000
	s_addc_u32 s7, s7, 0
	global_load_dword v136, v[32:33], off offset:32
	global_load_dword v105, v47, s[6:7] nt
	s_add_u32 s6, s6, 0xd000
	s_addc_u32 s7, s7, 0
	global_load_dword v137, v[32:33], off offset:40
	global_load_dword v106, v47, s[6:7] nt
	s_add_u32 s6, s6, 0xd000
	s_addc_u32 s7, s7, 0
	global_load_dword v138, v[32:33], off offset:48
	global_load_dword v107, v47, s[6:7] nt
	s_add_u32 s6, s6, 0xd000
	s_addc_u32 s7, s7, 0
	global_load_dword v139, v[32:33], off offset:56
	global_load_dword v108, v47, s[6:7] nt
	s_add_u32 s6, s6, 0xd000
	s_addc_u32 s7, s7, 0
	global_load_dword v140, v[32:33], off offset:64
	global_load_dword v109, v47, s[6:7] nt
	s_add_u32 s6, s6, 0xd000
	s_addc_u32 s7, s7, 0
	global_load_dword v141, v[32:33], off offset:72
	global_load_dword v110, v47, s[6:7] nt
	s_add_u32 s6, s6, 0xd000
	s_addc_u32 s7, s7, 0
	global_load_dword v142, v[32:33], off offset:80
	global_load_dword v111, v47, s[6:7] nt
	s_add_u32 s6, s6, 0xd000
	s_addc_u32 s7, s7, 0
	global_load_dword v143, v[32:33], off offset:88
	global_load_dword v112, v47, s[6:7] nt
	s_add_u32 s6, s6, 0xd000
	s_addc_u32 s7, s7, 0
	global_load_dword v144, v[32:33], off offset:96
	global_load_dword v113, v47, s[6:7] nt
	s_add_u32 s6, s6, 0xd000
	s_addc_u32 s7, s7, 0
	global_load_dword v145, v[32:33], off offset:104
	global_load_dword v114, v47, s[6:7] nt
	s_add_u32 s6, s6, 0xd000
	s_addc_u32 s7, s7, 0
	global_load_dword v146, v[32:33], off offset:112
	global_load_dword v115, v47, s[6:7] nt
	s_add_u32 s6, s6, 0xd000
	s_addc_u32 s7, s7, 0
	global_load_dword v147, v[32:33], off offset:120
	global_load_dword v116, v47, s[6:7] nt
	s_add_u32 s6, s6, 0xd000
	s_addc_u32 s7, s7, 0
	global_load_dword v148, v[32:33], off offset:128
	s_waitcnt vmcnt(32)
; __device__ __forceinline__ void p0_transpose_item(const float* W, int K, int N, bf16_t* WT, LAS float* scr, int item, int lane, const float* kscale) {
;     ...
;     for (int i = 0; i < 32; ++i) { const int kk = 2 * i + (lane >> 5); scr[kk * 33 + (lane & 31)] = W[(size_t)(k0 + kk) * N + n0 + (lane & 31)] * (kscale ? kscale[k0 + kk] : 1.0f); }
	v_mul_f32_e32 v100, v100, v132
	ds_write_b32 v39, v100 offset:0
	global_load_dword v117, v47, s[6:7] nt
	s_add_u32 s6, s6, 0xd000
	s_addc_u32 s7, s7, 0
	global_load_dword v149, v[32:33], off offset:136
	s_waitcnt vmcnt(32)
	v_mul_f32_e32 v101, v101, v133
	ds_write_b32 v39, v101 offset:264
	global_load_dword v118, v47, s[6:7] nt
	s_add_u32 s6, s6, 0xd000
	s_addc_u32 s7, s7, 0
	global_load_dword v150, v[32:33], off offset:144
	s_waitcnt vmcnt(32)
	v_mul_f32_e32 v102, v102, v134
	ds_write_b32 v39, v102 offset:528
	global_load_dword v119, v47, s[6:7] nt
	s_add_u32 s6, s6, 0xd000
	s_addc_u32 s7, s7, 0
	global_load_dword v151, v[32:33], off offset:152
	s_waitcnt vmcnt(32)
	v_mul_f32_e32 v103, v103, v135
	ds_write_b32 v39, v103 offset:792
	global_load_dword v120, v47, s[6:7] nt
	s_add_u32 s6, s6, 0xd000
	s_addc_u32 s7, s7, 0
	global_load_dword v152, v[32:33], off offset:160
	s_waitcnt vmcnt(32)
	v_mul_f32_e32 v104, v104, v136
	ds_write_b32 v39, v104 offset:1056
	global_load_dword v121, v47, s[6:7] nt
	s_add_u32 s6, s6, 0xd000
	s_addc_u32 s7, s7, 0
	global_load_dword v153, v[32:33], off offset:168
	s_waitcnt vmcnt(32)
	v_mul_f32_e32 v105, v105, v137
	ds_write_b32 v39, v105 offset:1320
	global_load_dword v122, v47, s[6:7] nt
	s_add_u32 s6, s6, 0xd000
	s_addc_u32 s7, s7, 0
	global_load_dword v154, v[32:33], off offset:176
	s_waitcnt vmcnt(32)
	v_mul_f32_e32 v106, v106, v138
	ds_write_b32 v39, v106 offset:1584
	global_load_dword v123, v47, s[6:7] nt
	s_add_u32 s6, s6, 0xd000
	s_addc_u32 s7, s7, 0
	global_load_dword v155, v[32:33], off offset:184
	s_waitcnt vmcnt(32)
	v_mul_f32_e32 v107, v107, v139
	ds_write_b32 v39, v107 offset:1848
	global_load_dword v124, v47, s[6:7] nt
	s_add_u32 s6, s6, 0xd000
	s_addc_u32 s7, s7, 0
	global_load_dword v156, v[32:33], off offset:192
	s_waitcnt vmcnt(32)
	v_mul_f32_e32 v108, v108, v140
	ds_write_b32 v39, v108 offset:2112
	global_load_dword v125, v47, s[6:7] nt
	s_add_u32 s6, s6, 0xd000
	s_addc_u32 s7, s7, 0
	global_load_dword v157, v[32:33], off offset:200
	s_waitcnt vmcnt(32)
	v_mul_f32_e32 v109, v109, v141
	ds_write_b32 v39, v109 offset:2376
	global_load_dword v126, v47, s[6:7] nt
	s_add_u32 s6, s6, 0xd000
	s_addc_u32 s7, s7, 0
	global_load_dword v158, v[32:33], off offset:208
	s_waitcnt vmcnt(32)
	v_mul_f32_e32 v110, v110, v142
	ds_write_b32 v39, v110 offset:2640
	global_load_dword v127, v47, s[6:7] nt
	s_add_u32 s6, s6, 0xd000
	s_addc_u32 s7, s7, 0
	global_load_dword v159, v[32:33], off offset:216
	s_waitcnt vmcnt(32)
	v_mul_f32_e32 v111, v111, v143
	ds_write_b32 v39, v111 offset:2904
	global_load_dword v128, v47, s[6:7] nt
	s_add_u32 s6, s6, 0xd000
	s_addc_u32 s7, s7, 0
	global_load_dword v160, v[32:33], off offset:224
	s_waitcnt vmcnt(32)
	v_mul_f32_e32 v112, v112, v144
	ds_write_b32 v39, v112 offset:3168
	global_load_dword v129, v47, s[6:7] nt
	s_add_u32 s6, s6, 0xd000
	s_addc_u32 s7, s7, 0
	global_load_dword v161, v[32:33], off offset:232
	s_waitcnt vmcnt(32)
	v_mul_f32_e32 v113, v113, v145
	ds_write_b32 v39, v113 offset:3432
	global_load_dword v130, v47, s[6:7] nt
	s_add_u32 s6, s6, 0xd000
	s_addc_u32 s7, s7, 0
	global_load_dword v162, v[32:33], off offset:240
	s_waitcnt vmcnt(32)
	v_mul_f32_e32 v114, v114, v146
	ds_write_b32 v39, v114 offset:3696
	global_load_dword v131, v47, s[6:7] nt
	global_load_dword v163, v[32:33], off offset:248
	s_waitcnt vmcnt(32)
	v_mul_f32_e32 v115, v115, v147
	ds_write_b32 v39, v115 offset:3960
	s_waitcnt vmcnt(30)
	v_mul_f32_e32 v116, v116, v148
	ds_write_b32 v39, v116 offset:4224
	s_waitcnt vmcnt(28)
	v_mul_f32_e32 v117, v117, v149
	ds_write_b32 v39, v117 offset:4488
	s_waitcnt vmcnt(26)
	v_mul_f32_e32 v118, v118, v150
	ds_write_b32 v39, v118 offset:4752
	s_waitcnt vmcnt(24)
	v_mul_f32_e32 v119, v119, v151
	ds_write_b32 v39, v119 offset:5016
	s_waitcnt vmcnt(22)
	v_mul_f32_e32 v120, v120, v152
	ds_write_b32 v39, v120 offset:5280
	s_waitcnt vmcnt(20)
	v_mul_f32_e32 v121, v121, v153
	ds_write_b32 v39, v121 offset:5544
	s_waitcnt vmcnt(18)
	v_mul_f32_e32 v122, v122, v154
	ds_write_b32 v39, v122 offset:5808
	s_waitcnt vmcnt(16)
	v_mul_f32_e32 v123, v123, v155
	ds_write_b32 v39, v123 offset:6072
	s_waitcnt vmcnt(14)
	v_mul_f32_e32 v124, v124, v156
	ds_write_b32 v39, v124 offset:6336
	s_waitcnt vmcnt(12)
	v_mul_f32_e32 v125, v125, v157
	ds_write_b32 v39, v125 offset:6600
	s_waitcnt vmcnt(10)
	v_mul_f32_e32 v126, v126, v158
	ds_write_b32 v39, v126 offset:6864
	s_waitcnt vmcnt(8)
	v_mul_f32_e32 v127, v127, v159
	ds_write_b32 v39, v127 offset:7128
	s_waitcnt vmcnt(6)
	v_mul_f32_e32 v128, v128, v160
	ds_write_b32 v39, v128 offset:7392
	s_waitcnt vmcnt(4)
	v_mul_f32_e32 v129, v129, v161
	ds_write_b32 v39, v129 offset:7656
	s_waitcnt vmcnt(2)
	v_mul_f32_e32 v130, v130, v162
	ds_write_b32 v39, v130 offset:7920
	s_waitcnt vmcnt(0)
	v_mul_f32_e32 v131, v131, v163
	ds_write_b32 v39, v131 offset:8184
	s_branch .LBB0_224

; __device__ __forceinline__ unsigned pk2(float lo, float hi) { unsigned r; asm("v_cvt_pk_bf16_f32 %0, %1, %2" : "=v"(r) : "v"(lo), "v"(hi)); return r; }
; __device__ __forceinline__ float bflo(unsigned w) { return __uint_as_float(w << 16); }
; __device__ __forceinline__ float bfhi(unsigned w) { return __uint_as_float(w & 0xffff0000u); }
; __global__ void __launch_bounds__(512, 2) mk_fwd(Params p) {
;     ...
;             for (int m = gw; m < M; m += NGW) {
;                 const f32x4* xr = (const f32x4*)(p.x + (size_t)m * DM) + lane; v2u* o8 = (v2u*)(XB + (size_t)m * DM) + lane; float sq = 0.f;
; #pragma unroll
;                 for (int j = 0; j < 8; ++j) { const f32x4 v = xr[64 * j]; v2u w; w.x = pk2(v.x, v.y); w.y = pk2(v.z, v.w); o8[64 * j] = w;
;                     const float r0 = bflo(w.x), r1 = bfhi(w.x), r2 = bflo(w.y), r3 = bfhi(w.y); sq += (r0 * r0 + r1 * r1) + (r2 * r2 + r3 * r3); }
;                 sq = wave_sum(sq); if (lane < 32) ROWSQ[(size_t)m * 32 + lane] = (lane == 0) ? sq : 0.f;
.LBB0_252:
	v_add_co_u32_e32 v12, vcc, 0xfffff000, v6
	s_nop 1
	v_addc_co_u32_e32 v13, vcc, -1, v7, vcc
	s_waitcnt lgkmcnt(0)
	global_load_dwordx4 v[8:11], v[12:13], off offset:-3072 nt
	s_waitcnt vmcnt(0)
	v_cvt_pk_bf16_f32 v14, v8, v9
	v_cvt_pk_bf16_f32 v15, v10, v11
	global_store_dwordx2 v[2:3], v[14:15], off offset:-2048
	v_lshlrev_b32_e32 v26, 16, v14
	v_and_b32_e32 v14, 0xffff0000, v14
	v_lshlrev_b32_e32 v27, 16, v15
	v_and_b32_e32 v15, 0xffff0000, v15
	v_mul_f32_e32 v14, v14, v14
	v_mul_f32_e32 v15, v15, v15
	global_load_dwordx4 v[8:11], v[12:13], off offset:-2048 nt
	s_waitcnt vmcnt(0)
	v_cvt_pk_bf16_f32 v16, v8, v9
	v_cvt_pk_bf16_f32 v17, v10, v11
	v_fmac_f32_e32 v14, v26, v26
	v_fmac_f32_e32 v15, v27, v27
	global_store_dwordx2 v[2:3], v[16:17], off offset:-1536
	v_add_f32_e32 v14, v14, v15
	v_lshlrev_b32_e32 v15, 16, v16
	v_and_b32_e32 v16, 0xffff0000, v16
	v_lshlrev_b32_e32 v26, 16, v17
	v_and_b32_e32 v17, 0xffff0000, v17
	v_mul_f32_e32 v16, v16, v16
	v_mul_f32_e32 v17, v17, v17
	v_fmac_f32_e32 v16, v15, v15
	v_fmac_f32_e32 v17, v26, v26
	global_load_dwordx4 v[8:11], v[12:13], off offset:-1024 nt
	s_waitcnt vmcnt(0)
	v_cvt_pk_bf16_f32 v12, v8, v9
	v_cvt_pk_bf16_f32 v13, v10, v11
	v_add_f32_e32 v15, v16, v17
	global_store_dwordx2 v[2:3], v[12:13], off offset:-1024
	v_add_f32_e32 v14, v14, v15
	v_lshlrev_b32_e32 v15, 16, v12
	v_and_b32_e32 v12, 0xffff0000, v12
	v_lshlrev_b32_e32 v16, 16, v13
	v_and_b32_e32 v13, 0xffff0000, v13
	v_mul_f32_e32 v12, v12, v12
	v_mul_f32_e32 v13, v13, v13
	v_fmac_f32_e32 v12, v15, v15
	v_fmac_f32_e32 v13, v16, v16
	v_add_f32_e32 v12, v12, v13
	global_load_dwordx4 v[8:11], v[6:7], off offset:-4096 nt
	s_waitcnt vmcnt(0)
	v_cvt_pk_bf16_f32 v18, v8, v9
	v_cvt_pk_bf16_f32 v19, v10, v11
	v_add_f32_e32 v12, v14, v12
	v_and_b32_e32 v14, 0xffff0000, v18
	v_and_b32_e32 v16, 0xffff0000, v19
	v_lshlrev_b32_e32 v13, 16, v18
	v_lshlrev_b32_e32 v15, 16, v19
	v_mul_f32_e32 v14, v14, v14
	v_mul_f32_e32 v16, v16, v16
	global_store_dwordx2 v[2:3], v[18:19], off offset:-512
	v_fmac_f32_e32 v14, v13, v13
	v_fmac_f32_e32 v16, v15, v15
	global_load_dwordx4 v[8:11], v[6:7], off offset:-3072 nt
	s_waitcnt vmcnt(0)
	v_cvt_pk_bf16_f32 v20, v8, v9
	v_cvt_pk_bf16_f32 v21, v10, v11
	v_add_f32_e32 v13, v14, v16
	v_and_b32_e32 v14, 0xffff0000, v20
	v_and_b32_e32 v16, 0xffff0000, v21
	v_add_f32_e32 v12, v12, v13
	v_lshlrev_b32_e32 v13, 16, v20
	v_lshlrev_b32_e32 v15, 16, v21
	v_mul_f32_e32 v14, v14, v14
	v_mul_f32_e32 v16, v16, v16
	global_store_dwordx2 v[2:3], v[20:21], off
	v_fmac_f32_e32 v14, v13, v13
	v_fmac_f32_e32 v16, v15, v15
	global_load_dwordx4 v[8:11], v[6:7], off offset:-2048 nt
	s_waitcnt vmcnt(0)
	v_cvt_pk_bf16_f32 v22, v8, v9
	v_cvt_pk_bf16_f32 v23, v10, v11
	v_add_f32_e32 v13, v14, v16
	v_and_b32_e32 v14, 0xffff0000, v22
	v_and_b32_e32 v16, 0xffff0000, v23
	v_add_f32_e32 v12, v12, v13
	v_lshlrev_b32_e32 v13, 16, v22
	v_lshlrev_b32_e32 v15, 16, v23
	v_mul_f32_e32 v14, v14, v14
	v_mul_f32_e32 v16, v16, v16
	global_store_dwordx2 v[2:3], v[22:23], off offset:512
	v_fmac_f32_e32 v14, v13, v13
	v_fmac_f32_e32 v16, v15, v15
	global_load_dwordx4 v[8:11], v[6:7], off offset:-1024 nt
	s_waitcnt vmcnt(0)
	v_cvt_pk_bf16_f32 v24, v8, v9
	v_cvt_pk_bf16_f32 v25, v10, v11
	v_add_f32_e32 v13, v14, v16
	v_and_b32_e32 v14, 0xffff0000, v24
	v_and_b32_e32 v16, 0xffff0000, v25
	v_add_f32_e32 v12, v12, v13
	v_lshlrev_b32_e32 v13, 16, v24
	v_lshlrev_b32_e32 v15, 16, v25
	v_mul_f32_e32 v14, v14, v14
	v_mul_f32_e32 v16, v16, v16
	global_store_dwordx2 v[2:3], v[24:25], off offset:1024
	v_fmac_f32_e32 v14, v13, v13
	v_fmac_f32_e32 v16, v15, v15
	global_load_dwordx4 v[8:11], v[6:7], off nt
	v_add_f32_e32 v13, v14, v16
	v_add_f32_e32 v14, v12, v13
	s_waitcnt vmcnt(0)
	v_cvt_pk_bf16_f32 v12, v8, v9
	v_cvt_pk_bf16_f32 v13, v10, v11
	v_cmp_lt_i32_e32 vcc, v220, v219
	v_and_b32_e32 v9, 0xffff0000, v12
	v_and_b32_e32 v11, 0xffff0000, v13
	v_lshlrev_b32_e32 v8, 16, v12
	v_lshlrev_b32_e32 v10, 16, v13
	v_mul_f32_e32 v9, v9, v9
	v_mul_f32_e32 v11, v11, v11
	v_fmac_f32_e32 v9, v8, v8
	v_fmac_f32_e32 v11, v10, v10
	v_cndmask_b32_e32 v0, v218, v220, vcc
	v_add_f32_e32 v8, v9, v11
	v_lshlrev_b32_e32 v0, 2, v0
	v_add_f32_e32 v8, v14, v8
	ds_bpermute_b32 v0, v0, v8
	v_cmp_lt_i32_e32 vcc, v221, v219
	global_store_dwordx2 v[2:3], v[12:13], off offset:1536
	s_waitcnt lgkmcnt(0)
	v_add_f32_e32 v0, v8, v0
	v_cndmask_b32_e32 v9, v218, v221, vcc
	v_lshlrev_b32_e32 v9, 2, v9
	ds_bpermute_b32 v8, v9, v0
	v_cmp_lt_i32_e32 vcc, v222, v219
	s_waitcnt lgkmcnt(0)
	v_add_f32_e32 v0, v0, v8
	v_cndmask_b32_e32 v9, v218, v222, vcc
	v_lshlrev_b32_e32 v9, 2, v9
	ds_bpermute_b32 v8, v9, v0
	v_cmp_lt_i32_e32 vcc, v223, v219
	s_waitcnt lgkmcnt(0)
	v_add_f32_e32 v0, v0, v8
	v_cndmask_b32_e32 v9, v218, v223, vcc
	v_lshlrev_b32_e32 v9, 2, v9
	ds_bpermute_b32 v8, v9, v0
	v_cmp_lt_i32_e32 vcc, v224, v219
	s_waitcnt lgkmcnt(0)
	v_add_f32_e32 v0, v0, v8
	v_cndmask_b32_e32 v9, v218, v224, vcc
	v_lshlrev_b32_e32 v9, 2, v9
	ds_bpermute_b32 v8, v9, v0
	v_cmp_lt_i32_e32 vcc, v225, v219
	s_waitcnt lgkmcnt(0)
	v_add_f32_e32 v0, v0, v8
	v_cndmask_b32_e32 v9, v218, v225, vcc
	v_lshlrev_b32_e32 v8, 2, v9
	ds_bpermute_b32 v8, v8, v0
	s_and_saveexec_b64 s[18:19], s[38:39]
	s_cbranch_execz .LBB0_251
	s_waitcnt lgkmcnt(0)
	v_add_f32_e32 v0, v0, v8
	v_cndmask_b32_e64 v0, 0, v0, s[40:41]
	global_store_dword v[4:5], v0, off
	s_branch .LBB0_251
